# adds attention K/V staging: k_norm gain vector loaded once per item at the top instead of re-loaded behind a scalar pointer load in each of the three staging passes
# speedup vs baseline: 1.0053x; 1.0053x over previous
; __device__ __forceinline__ void attn_phase(CArgs a, int l, LAS unsigned char* lds, int tid, int lane, int wave, int G, int bx) {
;     ...
;     for (int it = (bx + 64) % G; it < 1088; it += G) {
;         int ll = l; asm volatile("" : "+s"(ll));
;         const bool pr = it < 1024; const int half = it & 1;
;         const int bc = pr ? (it >> 1) : 0, c = bc & 255, b = bc >> 8, sb = pr ? 0 : ((it - 1024) >> 1);
;         const int token0 = (pr ? bc * 64 : TP + sb * 64) + half * 32;
;         __syncthreads();
;     ...
;                 for (int j = 0; j < 16; ++j) kv[j] = kv[j] * rs * a->in[23][ll * 64 + d0 + j]; }
.LBB0_277:
	s_cmpk_gt_i32 s20, 0x3ff
	s_cselect_b64 s[6:7], -1, 0
	s_ashr_i32 s2, s20, 1
	s_cmpk_lt_i32 s20, 0x400
	s_cselect_b64 s[8:9], -1, 0
	s_and_b64 s[0:1], s[8:9], exec
	v_readlane_b32 s88, v254, 24
	s_cselect_b32 s14, s2, 0
	s_and_b64 vcc, exec, s[6:7]
	s_nop 0
	s_barrier
	s_lshl_b32 s96, s88, 6
	v_or_b32_e32 v114, s96, v151
	v_ashrrev_i32_e32 v115, 31, v114
	s_load_dwordx2 s[96:97], s[92:93], 0xb8
	s_waitcnt lgkmcnt(0)
	v_lshl_add_u64 v[114:115], v[114:115], 2, s[96:97]
	global_load_dwordx4 v[118:121], v[114:115], off offset:16
	global_load_dwordx4 v[122:125], v[114:115], off offset:32
	global_load_dwordx4 v[126:129], v[114:115], off offset:48
	global_load_dwordx4 v[114:117], v[114:115], off
	s_cbranch_vccz .LBB0_279
	v_readlane_b32 s0, v255, 32
	v_readlane_b32 s1, v255, 33
	s_mov_b64 s[2:3], 0
	s_and_b64 s[0:1], s[0:1], exec
	s_branch .LBB0_280

; __device__ __forceinline__ void unpack8(u32x4 w, float* f) { f[0] = bflo(w.x); f[1] = bfhi(w.x); f[2] = bflo(w.y); f[3] = bfhi(w.y); f[4] = bflo(w.z); f[5] = bfhi(w.z); f[6] = bflo(w.w); f[7] = bfhi(w.w); }
; __device__ __forceinline__ void attn_phase(CArgs a, int l, LAS unsigned char* lds, int tid, int lane, int wave, int G, int bx) {
;     ...
;         for (int pass = 0; pass < 3; ++pass) {
;             const int idx = tid + 512 * pass, row = idx >> 2, qd = idx & 3, kvh = row >= 192 ? 1 : 0, s = row - 192 * kvh, d0 = qd * 16;
;             float kv[16], vv[16]; bool fromproj = false;
;             if (pr) fromproj = (c * 64 - 128 + s) >= 0; else fromproj = s >= 128;
;             if (fromproj) { unpack8(rk[pass][0], kv); unpack8(rk[pass][1], kv + 8); unpack8(rv[pass][0], vv); unpack8(rv[pass][1], vv + 8); }
;             else if (!pr) { const size_t co = ((size_t)((ll * 32 + sb) * 128 + s) * 2 + kvh) * 64 + d0;
; #pragma unroll
;                 for (int q = 0; q < 4; ++q) { const f32x4 k4 = *(const f32x4*)(a->in[2] + co + 4 * q), v4 = *(const f32x4*)(a->in[3] + co + 4 * q);
; #pragma unroll
;                     for (int j = 0; j < 4; ++j) { kv[4 * q + j] = k4[j]; vv[4 * q + j] = v4[j]; } }
;             } else {
; #pragma unroll
;                 for (int j = 0; j < 16; ++j) { kv[j] = 0.f; vv[j] = 0.f; } }
;             float ss = 0.f;
; #pragma unroll
;             for (int j = 0; j < 16; ++j) ss += kv[j] * kv[j];
;             ss += __shfl_xor(ss, 1); ss += __shfl_xor(ss, 2);
;             if (fromproj) { const float rs = rsqrtf(ss * (1.0f / 64.0f) + EPS);
; #pragma unroll
;                 for (int j = 0; j < 16; ++j) kv[j] = kv[j] * rs * a->in[23][ll * 64 + d0 + j]; }
.LBB0_301:
	s_or_b64 exec, exec, s[10:11]
	v_xor_b32_e32 v32, 1, v163
	v_cmp_lt_i32_e32 vcc, v32, v167
	v_xor_b32_e32 v34, 2, v163
	s_lshl_b32 s10, s88, 6
	v_cndmask_b32_e32 v32, v163, v32, vcc
	v_lshlrev_b32_e32 v38, 2, v32
	s_waitcnt vmcnt(7)
	v_mul_f32_e32 v32, v25, v25
	v_fmac_f32_e32 v32, v24, v24
	v_fmac_f32_e32 v32, v26, v26
	v_fmac_f32_e32 v32, v27, v27
	s_waitcnt vmcnt(6)
	v_fmac_f32_e32 v32, v12, v12
	v_fmac_f32_e32 v32, v13, v13
	v_fmac_f32_e32 v32, v14, v14
	v_fmac_f32_e32 v32, v15, v15
	s_waitcnt vmcnt(5)
	v_fmac_f32_e32 v32, v4, v4
	v_fmac_f32_e32 v32, v5, v5
	v_fmac_f32_e32 v32, v6, v6
	v_fmac_f32_e32 v32, v7, v7
	s_waitcnt vmcnt(4)
	v_fmac_f32_e32 v32, v0, v0
	v_fmac_f32_e32 v32, v1, v1
	v_fmac_f32_e32 v32, v2, v2
	v_fmac_f32_e32 v32, v3, v3
	ds_bpermute_b32 v33, v38, v32
	v_cmp_lt_i32_e32 vcc, v34, v167
	s_nop 1
	v_cndmask_b32_e32 v34, v163, v34, vcc
	v_lshlrev_b32_e32 v39, 2, v34
	s_waitcnt lgkmcnt(0)
	v_add_f32_e32 v34, v32, v33
	ds_bpermute_b32 v35, v39, v34
	v_or_b32_e32 v32, s10, v151
	v_ashrrev_i32_e32 v33, 31, v32
	s_and_saveexec_b64 s[12:13], s[4:5]
	s_cbranch_execz .LBB0_303
	s_waitcnt lgkmcnt(0)
	v_add_f32_e32 v34, v34, v35
	v_fmamk_f32 v34, v34, 0x3c800000, v162
	v_cmp_gt_f32_e32 vcc, s91, v34
	v_mul_f32_e32 v35, 0x4b800000, v34
	v_cndmask_b32_e32 v34, v34, v35, vcc
	v_rsq_f32_e32 v34, v34
	s_waitcnt lgkmcnt(0)
	v_mul_f32_e32 v35, 0x45800000, v34
	v_cndmask_b32_e32 v52, v34, v35, vcc
	v_mov_b32_e32 v34, v114
	v_mov_b32_e32 v35, v115
	v_mov_b32_e32 v36, v116
	v_mov_b32_e32 v37, v117
	v_mov_b32_e32 v40, v118
	v_mov_b32_e32 v41, v119
	v_mov_b32_e32 v42, v120
	v_mov_b32_e32 v43, v121
	v_mov_b32_e32 v44, v122
	v_mov_b32_e32 v45, v123
	v_mov_b32_e32 v46, v124
	v_mov_b32_e32 v47, v125
	s_nop 0
	v_mov_b32_e32 v48, v126
	v_mov_b32_e32 v49, v127
	v_mov_b32_e32 v50, v128
	v_mov_b32_e32 v51, v129
	v_pk_mul_f32 v[24:25], v[24:25], v[52:53] op_sel_hi:[1,0]
	v_pk_mul_f32 v[26:27], v[26:27], v[52:53] op_sel_hi:[1,0]
	v_pk_mul_f32 v[12:13], v[12:13], v[52:53] op_sel_hi:[1,0]
	v_pk_mul_f32 v[14:15], v[14:15], v[52:53] op_sel_hi:[1,0]
	v_pk_mul_f32 v[4:5], v[4:5], v[52:53] op_sel_hi:[1,0]
	v_pk_mul_f32 v[6:7], v[6:7], v[52:53] op_sel_hi:[1,0]
	v_pk_mul_f32 v[0:1], v[0:1], v[52:53] op_sel_hi:[1,0]
	v_pk_mul_f32 v[2:3], v[2:3], v[52:53] op_sel_hi:[1,0]
	s_waitcnt vmcnt(3)
	v_pk_mul_f32 v[26:27], v[26:27], v[36:37]
	s_waitcnt vmcnt(2)
	v_pk_mul_f32 v[14:15], v[14:15], v[42:43]
	s_waitcnt vmcnt(1)
	v_pk_mul_f32 v[6:7], v[6:7], v[46:47]
	s_waitcnt vmcnt(0)
	v_pk_mul_f32 v[2:3], v[2:3], v[50:51]
	v_pk_mul_f32 v[0:1], v[0:1], v[48:49]
	v_pk_mul_f32 v[4:5], v[4:5], v[44:45]
	v_pk_mul_f32 v[12:13], v[12:13], v[40:41]
	v_pk_mul_f32 v[24:25], v[24:25], v[34:35]

; __device__ __forceinline__ void attn_phase(CArgs a, int l, LAS unsigned char* lds, int tid, int lane, int wave, int G, int bx) {
;     ...
;             float ss = 0.f;
; #pragma unroll
;             for (int j = 0; j < 16; ++j) ss += kv[j] * kv[j];
;             ss += __shfl_xor(ss, 1); ss += __shfl_xor(ss, 2);
;             if (fromproj) { const float rs = rsqrtf(ss * (1.0f / 64.0f) + EPS);
; #pragma unroll
;                 for (int j = 0; j < 16; ++j) kv[j] = kv[j] * rs * a->in[23][ll * 64 + d0 + j]; }
.LBB0_321:
	s_or_b64 exec, exec, s[6:7]
	s_waitcnt vmcnt(7)
	v_mul_f32_e32 v34, v25, v25
	v_fmac_f32_e32 v34, v24, v24
	v_fmac_f32_e32 v34, v26, v26
	v_fmac_f32_e32 v34, v27, v27
	s_waitcnt vmcnt(6)
	v_fmac_f32_e32 v34, v12, v12
	v_fmac_f32_e32 v34, v13, v13
	v_fmac_f32_e32 v34, v14, v14
	v_fmac_f32_e32 v34, v15, v15
	s_waitcnt vmcnt(5)
	v_fmac_f32_e32 v34, v4, v4
	v_fmac_f32_e32 v34, v5, v5
	v_fmac_f32_e32 v34, v6, v6
	v_fmac_f32_e32 v34, v7, v7
	s_waitcnt vmcnt(4)
	v_fmac_f32_e32 v34, v0, v0
	v_fmac_f32_e32 v34, v1, v1
	v_fmac_f32_e32 v34, v2, v2
	v_fmac_f32_e32 v34, v3, v3
	ds_bpermute_b32 v35, v38, v34
	s_waitcnt lgkmcnt(0)
	v_add_f32_e32 v34, v34, v35
	ds_bpermute_b32 v35, v39, v34
	s_and_saveexec_b64 s[6:7], s[4:5]
	s_cbranch_execz .LBB0_323
	s_waitcnt lgkmcnt(0)
	v_add_f32_e32 v34, v34, v35
	v_fmamk_f32 v34, v34, 0x3c800000, v162
	v_cmp_gt_f32_e32 vcc, s91, v34
	v_mul_f32_e32 v35, 0x4b800000, v34
	v_cndmask_b32_e32 v34, v34, v35, vcc
	v_rsq_f32_e32 v34, v34
	s_waitcnt lgkmcnt(0)
	v_mul_f32_e32 v35, 0x45800000, v34
	v_cndmask_b32_e32 v52, v34, v35, vcc
	v_mov_b32_e32 v34, v114
	v_mov_b32_e32 v35, v115
	v_mov_b32_e32 v36, v116
	v_mov_b32_e32 v37, v117
	v_mov_b32_e32 v40, v118
	v_mov_b32_e32 v41, v119
	v_mov_b32_e32 v42, v120
	v_mov_b32_e32 v43, v121
	v_mov_b32_e32 v44, v122
	v_mov_b32_e32 v45, v123
	v_mov_b32_e32 v46, v124
	v_mov_b32_e32 v47, v125
	s_nop 0
	v_mov_b32_e32 v48, v126
	v_mov_b32_e32 v49, v127
	v_mov_b32_e32 v50, v128
	v_mov_b32_e32 v51, v129
	v_pk_mul_f32 v[24:25], v[24:25], v[52:53] op_sel_hi:[1,0]
	v_pk_mul_f32 v[26:27], v[26:27], v[52:53] op_sel_hi:[1,0]
	v_pk_mul_f32 v[12:13], v[12:13], v[52:53] op_sel_hi:[1,0]
	v_pk_mul_f32 v[14:15], v[14:15], v[52:53] op_sel_hi:[1,0]
	v_pk_mul_f32 v[4:5], v[4:5], v[52:53] op_sel_hi:[1,0]
	v_pk_mul_f32 v[6:7], v[6:7], v[52:53] op_sel_hi:[1,0]
	v_pk_mul_f32 v[0:1], v[0:1], v[52:53] op_sel_hi:[1,0]
	v_pk_mul_f32 v[2:3], v[2:3], v[52:53] op_sel_hi:[1,0]
	s_waitcnt vmcnt(3)
	v_pk_mul_f32 v[26:27], v[26:27], v[36:37]
	s_waitcnt vmcnt(2)
	v_pk_mul_f32 v[14:15], v[14:15], v[42:43]
	s_waitcnt vmcnt(1)
	v_pk_mul_f32 v[6:7], v[6:7], v[46:47]
	s_waitcnt vmcnt(0)
	v_pk_mul_f32 v[2:3], v[2:3], v[50:51]
	v_pk_mul_f32 v[0:1], v[0:1], v[48:49]
	v_pk_mul_f32 v[4:5], v[4:5], v[44:45]
	v_pk_mul_f32 v[12:13], v[12:13], v[40:41]
	v_pk_mul_f32 v[24:25], v[24:25], v[34:35]

; __device__ __forceinline__ void attn_phase(CArgs a, int l, LAS unsigned char* lds, int tid, int lane, int wave, int G, int bx) {
;     ...
;             float ss = 0.f;
; #pragma unroll
;             for (int j = 0; j < 16; ++j) ss += kv[j] * kv[j];
;             ss += __shfl_xor(ss, 1); ss += __shfl_xor(ss, 2);
;             if (fromproj) { const float rs = rsqrtf(ss * (1.0f / 64.0f) + EPS);
; #pragma unroll
;                 for (int j = 0; j < 16; ++j) kv[j] = kv[j] * rs * a->in[23][ll * 64 + d0 + j]; }
.LBB0_341:
	s_or_b64 exec, exec, s[18:19]
	s_waitcnt vmcnt(7)
	v_mul_f32_e32 v34, v25, v25
	v_fmac_f32_e32 v34, v24, v24
	v_fmac_f32_e32 v34, v26, v26
	v_fmac_f32_e32 v34, v27, v27
	s_waitcnt vmcnt(6)
	v_fmac_f32_e32 v34, v12, v12
	v_fmac_f32_e32 v34, v13, v13
	v_fmac_f32_e32 v34, v14, v14
	v_fmac_f32_e32 v34, v15, v15
	s_waitcnt vmcnt(5)
	v_fmac_f32_e32 v34, v4, v4
	v_fmac_f32_e32 v34, v5, v5
	v_fmac_f32_e32 v34, v6, v6
	v_fmac_f32_e32 v34, v7, v7
	s_waitcnt vmcnt(4)
	v_fmac_f32_e32 v34, v0, v0
	v_fmac_f32_e32 v34, v1, v1
	v_fmac_f32_e32 v34, v2, v2
	v_fmac_f32_e32 v34, v3, v3
	ds_bpermute_b32 v35, v38, v34
	s_waitcnt lgkmcnt(0)
	v_add_f32_e32 v34, v34, v35
	ds_bpermute_b32 v35, v39, v34
	s_and_saveexec_b64 s[18:19], s[4:5]
	s_cbranch_execz .LBB0_343
	s_waitcnt lgkmcnt(0)
	v_add_f32_e32 v34, v34, v35
	v_fmamk_f32 v34, v34, 0x3c800000, v162
	v_cmp_gt_f32_e32 vcc, s91, v34
	v_mul_f32_e32 v35, 0x4b800000, v34
	v_cndmask_b32_e32 v34, v34, v35, vcc
	v_rsq_f32_e32 v34, v34
	s_waitcnt lgkmcnt(0)
	v_mul_f32_e32 v35, 0x45800000, v34
	v_cndmask_b32_e32 v48, v34, v35, vcc
	v_mov_b32_e32 v32, v114
	v_mov_b32_e32 v33, v115
	v_mov_b32_e32 v34, v116
	v_mov_b32_e32 v35, v117
	v_mov_b32_e32 v36, v118
	v_mov_b32_e32 v37, v119
	v_mov_b32_e32 v38, v120
	v_mov_b32_e32 v39, v121
	v_mov_b32_e32 v40, v122
	v_mov_b32_e32 v41, v123
	v_mov_b32_e32 v42, v124
	v_mov_b32_e32 v43, v125
	s_nop 0
	v_mov_b32_e32 v44, v126
	v_mov_b32_e32 v45, v127
	v_mov_b32_e32 v46, v128
	v_mov_b32_e32 v47, v129
	v_pk_mul_f32 v[24:25], v[24:25], v[48:49] op_sel_hi:[1,0]
	v_pk_mul_f32 v[26:27], v[26:27], v[48:49] op_sel_hi:[1,0]
	v_pk_mul_f32 v[12:13], v[12:13], v[48:49] op_sel_hi:[1,0]
	v_pk_mul_f32 v[14:15], v[14:15], v[48:49] op_sel_hi:[1,0]
	v_pk_mul_f32 v[4:5], v[4:5], v[48:49] op_sel_hi:[1,0]
	v_pk_mul_f32 v[6:7], v[6:7], v[48:49] op_sel_hi:[1,0]
	v_pk_mul_f32 v[0:1], v[0:1], v[48:49] op_sel_hi:[1,0]
	v_pk_mul_f32 v[2:3], v[2:3], v[48:49] op_sel_hi:[1,0]
	s_waitcnt vmcnt(3)
	v_pk_mul_f32 v[26:27], v[26:27], v[34:35]
	s_waitcnt vmcnt(2)
	v_pk_mul_f32 v[14:15], v[14:15], v[38:39]
	s_waitcnt vmcnt(1)
	v_pk_mul_f32 v[6:7], v[6:7], v[42:43]
	s_waitcnt vmcnt(0)
	v_pk_mul_f32 v[2:3], v[2:3], v[46:47]
	v_pk_mul_f32 v[0:1], v[0:1], v[44:45]
	v_pk_mul_f32 v[4:5], v[4:5], v[40:41]
	v_pk_mul_f32 v[12:13], v[12:13], v[36:37]
	v_pk_mul_f32 v[24:25], v[24:25], v[32:33]
